# GEMM k-loops: next step's LDS fragment reads issued one per MFMA gap (not as a burst) with per-MFMA counted lgkmcnt waits
# speedup vs baseline: 1.0753x; 1.0208x over previous
; #define MFMA(a, b, c) __builtin_amdgcn_mfma_f32_32x32x16_bf16((a), (b), (c), 0, 0, 0)
; #define GEMM_ISSUE(KT, ST) do { const int k1_ = (KT) << 6; unsigned char* d_ = ldst + (ST) * STAGE; \
;         _Pragma("unroll") for (int j_ = 0; j_ < 4; ++j_) dma16(ap + (size_t)(64 * j_) * lda + k1_, d_ + j_ * 8192); \
;         _Pragma("unroll") for (int j_ = 0; j_ < NBW; ++j_) dma16(bp + bro[j_] + k1_, d_ + BOFF + j_ * 8192); } while (0)
; template <int NBW>
; DI void gemm_mainloop(f32x16 (&acc)[2][NBW], const bf16_t* A, size_t lda, int m0, const bf16_t* Bt, size_t ldb, int n0, int K, unsigned char* lds, bool pre = false, bool only_issue = false) {
;     ...
;     for (int kt = 0; kt < nk; ++kt) {
;         const unsigned char* st = lds + (kt & 1) * STAGE;
; #pragma unroll
;         for (int s = 0; s < 4; ++s) {
;             if (s == 1 && kt + 1 < nk) GEMM_ISSUE(kt + 1, (kt + 1) & 1);
;             bf16x8 a[2], b[NBW];
; #pragma unroll
;             for (int mb = 0; mb < 2; ++mb) a[mb] = *(const bf16x8*)(st + aofs + mb * 4096 + xo[s]);
; #pragma unroll
;             for (int nb = 0; nb < NBW; ++nb) b[nb] = *(const bf16x8*)(st + bofs + nb * 4096 + xo[s]);
; #pragma unroll
;             for (int mb = 0; mb < 2; ++mb)
; #pragma unroll
;                 for (int nb = 0; nb < NBW; ++nb) acc[mb][nb] = MFMA(a[mb], b[nb], acc[mb][nb]);
;         }
;         __syncthreads();
.Lp1_kloop:
	s_waitcnt lgkmcnt(4)
	v_mfma_f32_32x32x16_bf16 v[114:129], v[224:227], v[232:235], v[114:129]
	v_add_u32_e32 v252, v138, v144
	v_add_u32_e32 v253, v149, v144
	ds_read_b128 v[150:153], v252
	s_waitcnt lgkmcnt(4)
	v_mfma_f32_32x32x16_bf16 v[82:97], v[224:227], v[236:239], v[82:97]
	ds_read_b128 v[170:173], v253 offset:32768
	s_waitcnt lgkmcnt(4)
	v_mfma_f32_32x32x16_bf16 v[98:113], v[224:227], v[240:243], v[98:113]
	ds_read_b128 v[174:177], v253 offset:36864
	s_waitcnt lgkmcnt(4)
	v_mfma_f32_32x32x16_bf16 v[66:81], v[224:227], v[244:247], v[66:81]
	ds_read_b128 v[178:181], v253 offset:40960
	s_waitcnt lgkmcnt(4)
	v_mfma_f32_32x32x16_bf16 v[50:65], v[228:231], v[232:235], v[50:65]
	ds_read_b128 v[182:185], v253 offset:45056
	v_mfma_f32_32x32x16_bf16 v[18:33], v[228:231], v[236:239], v[18:33]
	ds_read_b128 v[166:169], v252 offset:4096
	v_mfma_f32_32x32x16_bf16 v[34:49], v[228:231], v[240:243], v[34:49]
	v_mfma_f32_32x32x16_bf16 v[2:17], v[228:231], v[244:247], v[2:17]
	s_waitcnt lgkmcnt(4)
	v_mfma_f32_32x32x16_bf16 v[114:129], v[150:153], v[170:173], v[114:129]
	v_add_u32_e32 v252, v138, v145
	v_add_u32_e32 v253, v149, v145
	ds_read_b128 v[224:227], v252
	s_waitcnt lgkmcnt(4)
	v_mfma_f32_32x32x16_bf16 v[82:97], v[150:153], v[174:177], v[82:97]
	ds_read_b128 v[232:235], v253 offset:32768
	s_waitcnt lgkmcnt(4)
	v_mfma_f32_32x32x16_bf16 v[98:113], v[150:153], v[178:181], v[98:113]
	ds_read_b128 v[236:239], v253 offset:36864
	s_waitcnt lgkmcnt(4)
	v_mfma_f32_32x32x16_bf16 v[66:81], v[150:153], v[182:185], v[66:81]
	ds_read_b128 v[240:243], v253 offset:40960
	s_waitcnt lgkmcnt(4)
	v_mfma_f32_32x32x16_bf16 v[50:65], v[166:169], v[170:173], v[50:65]
	ds_read_b128 v[244:247], v253 offset:45056
	v_mfma_f32_32x32x16_bf16 v[18:33], v[166:169], v[174:177], v[18:33]
	ds_read_b128 v[228:231], v252 offset:4096
	v_mfma_f32_32x32x16_bf16 v[34:49], v[166:169], v[178:181], v[34:49]
	v_mfma_f32_32x32x16_bf16 v[2:17], v[166:169], v[182:185], v[2:17]
	s_waitcnt lgkmcnt(4)
	v_mfma_f32_32x32x16_bf16 v[114:129], v[224:227], v[232:235], v[114:129]
	v_add_u32_e32 v252, v138, v146
	v_add_u32_e32 v253, v149, v146
	ds_read_b128 v[150:153], v252
	s_waitcnt lgkmcnt(4)
	v_mfma_f32_32x32x16_bf16 v[82:97], v[224:227], v[236:239], v[82:97]
	ds_read_b128 v[170:173], v253 offset:32768
	s_waitcnt lgkmcnt(4)
	v_mfma_f32_32x32x16_bf16 v[98:113], v[224:227], v[240:243], v[98:113]
	ds_read_b128 v[174:177], v253 offset:36864
	s_waitcnt lgkmcnt(4)
	v_mfma_f32_32x32x16_bf16 v[66:81], v[224:227], v[244:247], v[66:81]
	ds_read_b128 v[178:181], v253 offset:40960
	s_waitcnt lgkmcnt(4)
	v_mfma_f32_32x32x16_bf16 v[50:65], v[228:231], v[232:235], v[50:65]
	ds_read_b128 v[182:185], v253 offset:45056
	v_mfma_f32_32x32x16_bf16 v[18:33], v[228:231], v[236:239], v[18:33]
	ds_read_b128 v[166:169], v252 offset:4096
	v_mfma_f32_32x32x16_bf16 v[34:49], v[228:231], v[240:243], v[34:49]
	v_mfma_f32_32x32x16_bf16 v[2:17], v[228:231], v[244:247], v[2:17]
	v_xor_b32_e32 v138, 0x10000, v138
	v_xor_b32_e32 v149, 0x10000, v149
	s_waitcnt vmcnt(0) lgkmcnt(0)
	s_barrier
	s_cmp_eq_u32 s2, 0x800
	s_cbranch_scc1 .Lp1_klast
	s_cmp_eq_u32 s2, 0x780
	s_cbranch_scc1 .Lp1_knodma
	v_mfma_f32_32x32x16_bf16 v[114:129], v[150:153], v[170:173], v[114:129]
	v_add_u32_e32 v252, v138, v143
	v_add_u32_e32 v253, v149, v143
	ds_read_b128 v[224:227], v252
	s_and_b32 s19, s18, 0x10000
	v_add_u32_e32 v250, s19, v142
	v_lshl_add_u64 v[248:249], v[130:131], 0, s[2:3]
	s_nop 0
	v_readfirstlane_b32 s19, v250
	s_mov_b64 s[22:23], 0x1080
	v_lshl_add_u64 v[250:251], v[248:249], 0, s[22:23]
	s_mov_b32 m0, s19
	s_nop 0
	global_load_lds_dwordx4 v[250:251], off
	v_mfma_f32_32x32x16_bf16 v[82:97], v[150:153], v[174:177], v[82:97]
	ds_read_b128 v[232:235], v253 offset:32768
	s_mov_b64 s[22:23], 0x21080
	v_lshl_add_u64 v[250:251], v[248:249], 0, s[22:23]
	s_add_i32 m0, s19, 0x2000
	s_nop 0
	global_load_lds_dwordx4 v[250:251], off
	v_mfma_f32_32x32x16_bf16 v[98:113], v[150:153], v[178:181], v[98:113]
	ds_read_b128 v[236:239], v253 offset:36864
	s_mov_b64 s[22:23], 0x41080
	v_lshl_add_u64 v[250:251], v[248:249], 0, s[22:23]
	s_add_i32 m0, s19, 0x4000
	s_nop 0
	global_load_lds_dwordx4 v[250:251], off
	v_mfma_f32_32x32x16_bf16 v[66:81], v[150:153], v[182:185], v[66:81]
	ds_read_b128 v[240:243], v253 offset:40960
	s_mov_b64 s[22:23], 0x61080
	v_lshl_add_u64 v[250:251], v[248:249], 0, s[22:23]
	s_add_i32 m0, s19, 0x6000
	s_nop 0
	global_load_lds_dwordx4 v[250:251], off
	v_mfma_f32_32x32x16_bf16 v[50:65], v[166:169], v[170:173], v[50:65]
	ds_read_b128 v[244:247], v253 offset:45056
	v_lshl_add_u64 v[250:251], v[132:133], 0, s[2:3]
	s_add_i32 m0, s19, 0x8000
	s_nop 0
	global_load_lds_dwordx4 v[250:251], off
	v_mfma_f32_32x32x16_bf16 v[18:33], v[166:169], v[174:177], v[18:33]
	ds_read_b128 v[228:231], v252 offset:4096
	v_lshl_add_u64 v[250:251], v[134:135], 0, s[2:3]
	s_add_i32 m0, s19, 0xa000
	s_nop 0
	global_load_lds_dwordx4 v[250:251], off
	v_mfma_f32_32x32x16_bf16 v[34:49], v[166:169], v[178:181], v[34:49]
	v_lshl_add_u64 v[250:251], v[136:137], 0, s[2:3]
	s_add_i32 m0, s19, 0xc000
	s_nop 0
	global_load_lds_dwordx4 v[250:251], off
	v_mfma_f32_32x32x16_bf16 v[2:17], v[166:169], v[182:185], v[2:17]
	v_lshl_add_u64 v[250:251], v[140:141], 0, s[2:3]
	s_add_i32 m0, s19, 0xe000
	s_nop 0
	global_load_lds_dwordx4 v[250:251], off
	s_add_u32 s2, s2, 0x80
	s_addc_u32 s3, s3, 0
	s_add_i32 s18, s18, 0x10000
	s_branch .Lp1_kloop
.Lp1_knodma:
	v_mfma_f32_32x32x16_bf16 v[114:129], v[150:153], v[170:173], v[114:129]
	v_add_u32_e32 v252, v138, v143
	v_add_u32_e32 v253, v149, v143
	ds_read_b128 v[224:227], v252
	v_mfma_f32_32x32x16_bf16 v[82:97], v[150:153], v[174:177], v[82:97]
	ds_read_b128 v[232:235], v253 offset:32768
	v_mfma_f32_32x32x16_bf16 v[98:113], v[150:153], v[178:181], v[98:113]
	ds_read_b128 v[236:239], v253 offset:36864
	v_mfma_f32_32x32x16_bf16 v[66:81], v[150:153], v[182:185], v[66:81]
	ds_read_b128 v[240:243], v253 offset:40960
	v_mfma_f32_32x32x16_bf16 v[50:65], v[166:169], v[170:173], v[50:65]
	ds_read_b128 v[244:247], v253 offset:45056
	v_mfma_f32_32x32x16_bf16 v[18:33], v[166:169], v[174:177], v[18:33]
	ds_read_b128 v[228:231], v252 offset:4096
	v_mfma_f32_32x32x16_bf16 v[34:49], v[166:169], v[178:181], v[34:49]
	v_mfma_f32_32x32x16_bf16 v[2:17], v[166:169], v[182:185], v[2:17]
	s_add_u32 s2, s2, 0x80
	s_addc_u32 s3, s3, 0
	s_add_i32 s18, s18, 0x10000
	s_branch .Lp1_kloop

; #define MFMA(a, b, c) __builtin_amdgcn_mfma_f32_32x32x16_bf16((a), (b), (c), 0, 0, 0)
; #define GEMM_ISSUE(KT, ST) do { const int k1_ = (KT) << 6; unsigned char* d_ = ldst + (ST) * STAGE; \
;         _Pragma("unroll") for (int j_ = 0; j_ < 4; ++j_) dma16(ap + (size_t)(64 * j_) * lda + k1_, d_ + j_ * 8192); \
;         _Pragma("unroll") for (int j_ = 0; j_ < NBW; ++j_) dma16(bp + bro[j_] + k1_, d_ + BOFF + j_ * 8192); } while (0)
; template <int NBW>
; DI void gemm_mainloop(f32x16 (&acc)[2][NBW], const bf16_t* A, size_t lda, int m0, const bf16_t* Bt, size_t ldb, int n0, int K, unsigned char* lds, bool pre = false, bool only_issue = false) {
;     ...
;     for (int kt = 0; kt < nk; ++kt) {
;         const unsigned char* st = lds + (kt & 1) * STAGE;
; #pragma unroll
;         for (int s = 0; s < 4; ++s) {
;             if (s == 1 && kt + 1 < nk) GEMM_ISSUE(kt + 1, (kt + 1) & 1);
;             bf16x8 a[2], b[NBW];
; #pragma unroll
;             for (int mb = 0; mb < 2; ++mb) a[mb] = *(const bf16x8*)(st + aofs + mb * 4096 + xo[s]);
; #pragma unroll
;             for (int nb = 0; nb < NBW; ++nb) b[nb] = *(const bf16x8*)(st + bofs + nb * 4096 + xo[s]);
; #pragma unroll
;             for (int mb = 0; mb < 2; ++mb)
; #pragma unroll
;                 for (int nb = 0; nb < NBW; ++nb) acc[mb][nb] = MFMA(a[mb], b[nb], acc[mb][nb]);
;         }
;         __syncthreads();
.Lp4a_kloop:
	s_waitcnt lgkmcnt(2)
	v_mfma_f32_32x32x16_bf16 v[66:81], v[240:243], v[248:251], v[66:81]
	v_add_u32_e32 v65, v63, v58
	v_add_u32_e32 v88, v64, v58
	ds_read_b128 v[224:227], v65
	s_waitcnt lgkmcnt(2)
	v_mfma_f32_32x32x16_bf16 v[34:49], v[240:243], v[252:255], v[34:49]
	ds_read_b128 v[232:235], v88 offset:32768
	s_waitcnt lgkmcnt(2)
	v_mfma_f32_32x32x16_bf16 v[18:33], v[244:247], v[248:251], v[18:33]
	ds_read_b128 v[236:239], v88 offset:36864
	v_mfma_f32_32x32x16_bf16 v[2:17], v[244:247], v[252:255], v[2:17]
	ds_read_b128 v[228:231], v65 offset:4096
	s_waitcnt lgkmcnt(2)
	v_mfma_f32_32x32x16_bf16 v[66:81], v[224:227], v[232:235], v[66:81]
	v_add_u32_e32 v65, v63, v59
	v_add_u32_e32 v88, v64, v59
	ds_read_b128 v[240:243], v65
	s_waitcnt lgkmcnt(2)
	v_mfma_f32_32x32x16_bf16 v[34:49], v[224:227], v[236:239], v[34:49]
	ds_read_b128 v[248:251], v88 offset:32768
	s_waitcnt lgkmcnt(2)
	v_mfma_f32_32x32x16_bf16 v[18:33], v[228:231], v[232:235], v[18:33]
	ds_read_b128 v[252:255], v88 offset:36864
	v_mfma_f32_32x32x16_bf16 v[2:17], v[228:231], v[236:239], v[2:17]
	ds_read_b128 v[244:247], v65 offset:4096
	s_waitcnt lgkmcnt(2)
	v_mfma_f32_32x32x16_bf16 v[66:81], v[240:243], v[248:251], v[66:81]
	v_add_u32_e32 v65, v63, v60
	v_add_u32_e32 v88, v64, v60
	ds_read_b128 v[224:227], v65
	s_waitcnt lgkmcnt(2)
	v_mfma_f32_32x32x16_bf16 v[34:49], v[240:243], v[252:255], v[34:49]
	ds_read_b128 v[232:235], v88 offset:32768
	s_waitcnt lgkmcnt(2)
	v_mfma_f32_32x32x16_bf16 v[18:33], v[244:247], v[248:251], v[18:33]
	ds_read_b128 v[236:239], v88 offset:36864
	v_mfma_f32_32x32x16_bf16 v[2:17], v[244:247], v[252:255], v[2:17]
	ds_read_b128 v[228:231], v65 offset:4096
	v_xor_b32_e32 v63, 0x10000, v63
	v_xor_b32_e32 v64, 0x10000, v64
	s_waitcnt vmcnt(0) lgkmcnt(0)
	s_barrier
	s_cmp_eq_u32 s76, 0x800
	s_cbranch_scc1 .Lp4a_klast
	s_cmp_eq_u32 s76, 0x780
	s_cbranch_scc1 .Lp4a_knodma
	v_mfma_f32_32x32x16_bf16 v[66:81], v[224:227], v[232:235], v[66:81]
	v_add_u32_e32 v65, v63, v57
	v_add_u32_e32 v88, v64, v57
	ds_read_b128 v[240:243], v65
	s_and_b32 s71, s67, 0x10000
	v_add_u32_e32 v86, s71, v56
	v_lshl_add_u64 v[84:85], v[50:51], 0, s[76:77]
	s_nop 0
	v_readfirstlane_b32 s71, v86
	s_mov_b64 s[86:87], 0xea81080
	v_lshl_add_u64 v[86:87], v[84:85], 0, s[86:87]
	s_mov_b32 m0, s71
	s_nop 0
	global_load_lds_dwordx4 v[86:87], off
	v_mfma_f32_32x32x16_bf16 v[34:49], v[224:227], v[236:239], v[34:49]
	ds_read_b128 v[248:251], v88 offset:32768
	s_mov_b64 s[86:87], 0xeaa1080
	v_lshl_add_u64 v[86:87], v[84:85], 0, s[86:87]
	s_add_i32 m0, s71, 0x2000
	s_nop 0
	global_load_lds_dwordx4 v[86:87], off
	s_mov_b64 s[86:87], 0xeac1080
	v_lshl_add_u64 v[86:87], v[84:85], 0, s[86:87]
	s_add_i32 m0, s71, 0x4000
	s_nop 0
	global_load_lds_dwordx4 v[86:87], off
	v_mfma_f32_32x32x16_bf16 v[18:33], v[228:231], v[232:235], v[18:33]
	ds_read_b128 v[252:255], v88 offset:36864
	s_mov_b64 s[86:87], 0xeae1080
	v_lshl_add_u64 v[86:87], v[84:85], 0, s[86:87]
	s_add_i32 m0, s71, 0x6000
	s_nop 0
	global_load_lds_dwordx4 v[86:87], off
	v_mfma_f32_32x32x16_bf16 v[2:17], v[228:231], v[236:239], v[2:17]
	ds_read_b128 v[244:247], v65 offset:4096
	v_lshl_add_u64 v[86:87], v[52:53], 0, s[76:77]
	s_add_i32 m0, s71, 0x8000
	s_nop 0
	global_load_lds_dwordx4 v[86:87], off
	v_lshl_add_u64 v[86:87], v[54:55], 0, s[76:77]
	s_add_i32 m0, s71, 0xa000
	s_nop 0
	global_load_lds_dwordx4 v[86:87], off
	s_add_u32 s76, s76, 0x80
	s_addc_u32 s77, s77, 0
	s_add_i32 s67, s67, 0x10000
	s_branch .Lp4a_kloop
.Lp4a_knodma:
	v_mfma_f32_32x32x16_bf16 v[66:81], v[224:227], v[232:235], v[66:81]
	v_add_u32_e32 v65, v63, v57
	v_add_u32_e32 v88, v64, v57
	ds_read_b128 v[240:243], v65
	v_mfma_f32_32x32x16_bf16 v[34:49], v[224:227], v[236:239], v[34:49]
	ds_read_b128 v[248:251], v88 offset:32768
	v_mfma_f32_32x32x16_bf16 v[18:33], v[228:231], v[232:235], v[18:33]
	ds_read_b128 v[252:255], v88 offset:36864
	v_mfma_f32_32x32x16_bf16 v[2:17], v[228:231], v[236:239], v[2:17]
	ds_read_b128 v[244:247], v65 offset:4096
	s_add_u32 s76, s76, 0x80
	s_addc_u32 s77, s77, 0
	s_add_i32 s67, s67, 0x10000
	s_branch .Lp4a_kloop

; #define MFMA(a, b, c) __builtin_amdgcn_mfma_f32_32x32x16_bf16((a), (b), (c), 0, 0, 0)
; #define GEMM_ISSUE(KT, ST) do { const int k1_ = (KT) << 6; unsigned char* d_ = ldst + (ST) * STAGE; \
;         _Pragma("unroll") for (int j_ = 0; j_ < 4; ++j_) dma16(ap + (size_t)(64 * j_) * lda + k1_, d_ + j_ * 8192); \
;         _Pragma("unroll") for (int j_ = 0; j_ < NBW; ++j_) dma16(bp + bro[j_] + k1_, d_ + BOFF + j_ * 8192); } while (0)
; template <int NBW>
; DI void gemm_mainloop(f32x16 (&acc)[2][NBW], const bf16_t* A, size_t lda, int m0, const bf16_t* Bt, size_t ldb, int n0, int K, unsigned char* lds, bool pre = false, bool only_issue = false) {
;     ...
;     for (int kt = 0; kt < nk; ++kt) {
;         const unsigned char* st = lds + (kt & 1) * STAGE;
; #pragma unroll
;         for (int s = 0; s < 4; ++s) {
;             if (s == 1 && kt + 1 < nk) GEMM_ISSUE(kt + 1, (kt + 1) & 1);
;             bf16x8 a[2], b[NBW];
; #pragma unroll
;             for (int mb = 0; mb < 2; ++mb) a[mb] = *(const bf16x8*)(st + aofs + mb * 4096 + xo[s]);
; #pragma unroll
;             for (int nb = 0; nb < NBW; ++nb) b[nb] = *(const bf16x8*)(st + bofs + nb * 4096 + xo[s]);
; #pragma unroll
;             for (int mb = 0; mb < 2; ++mb)
; #pragma unroll
;                 for (int nb = 0; nb < NBW; ++nb) acc[mb][nb] = MFMA(a[mb], b[nb], acc[mb][nb]);
;         }
;         __syncthreads();
.Lp4b_kloop:
	s_waitcnt lgkmcnt(2)
	v_mfma_f32_32x32x16_bf16 v[114:129], v[240:243], v[248:251], v[114:129]
	v_add_u32_e32 v157, v134, v145
	v_add_u32_e32 v159, v155, v145
	ds_read_b128 v[224:227], v157
	s_waitcnt lgkmcnt(2)
	v_mfma_f32_32x32x16_bf16 v[98:113], v[240:243], v[252:255], v[98:113]
	ds_read_b128 v[232:235], v159 offset:32768
	s_waitcnt lgkmcnt(2)
	v_mfma_f32_32x32x16_bf16 v[82:97], v[244:247], v[248:251], v[82:97]
	ds_read_b128 v[236:239], v159 offset:36864
	v_mfma_f32_32x32x16_bf16 v[50:65], v[244:247], v[252:255], v[50:65]
	ds_read_b128 v[228:231], v157 offset:4096
	s_waitcnt lgkmcnt(2)
	v_mfma_f32_32x32x16_bf16 v[114:129], v[224:227], v[232:235], v[114:129]
	v_add_u32_e32 v157, v134, v147
	v_add_u32_e32 v159, v155, v147
	ds_read_b128 v[240:243], v157
	s_waitcnt lgkmcnt(2)
	v_mfma_f32_32x32x16_bf16 v[98:113], v[224:227], v[236:239], v[98:113]
	ds_read_b128 v[248:251], v159 offset:32768
	s_waitcnt lgkmcnt(2)
	v_mfma_f32_32x32x16_bf16 v[82:97], v[228:231], v[232:235], v[82:97]
	ds_read_b128 v[252:255], v159 offset:36864
	v_mfma_f32_32x32x16_bf16 v[50:65], v[228:231], v[236:239], v[50:65]
	ds_read_b128 v[244:247], v157 offset:4096
	s_waitcnt lgkmcnt(2)
	v_mfma_f32_32x32x16_bf16 v[114:129], v[240:243], v[248:251], v[114:129]
	v_add_u32_e32 v157, v134, v149
	v_add_u32_e32 v159, v155, v149
	ds_read_b128 v[224:227], v157
	s_waitcnt lgkmcnt(2)
	v_mfma_f32_32x32x16_bf16 v[98:113], v[240:243], v[252:255], v[98:113]
	ds_read_b128 v[232:235], v159 offset:32768
	s_waitcnt lgkmcnt(2)
	v_mfma_f32_32x32x16_bf16 v[82:97], v[244:247], v[248:251], v[82:97]
	ds_read_b128 v[236:239], v159 offset:36864
	v_mfma_f32_32x32x16_bf16 v[50:65], v[244:247], v[252:255], v[50:65]
	ds_read_b128 v[228:231], v157 offset:4096
	v_xor_b32_e32 v134, 0x10000, v134
	v_xor_b32_e32 v155, 0x10000, v155
	s_waitcnt vmcnt(0) lgkmcnt(0)
	s_barrier
	s_cmp_eq_u32 s72, 0x800
	s_cbranch_scc1 .Lp4b_klast
	s_cmp_eq_u32 s72, 0x780
	s_cbranch_scc1 .Lp4b_knodma
	v_mfma_f32_32x32x16_bf16 v[114:129], v[224:227], v[232:235], v[114:129]
	v_add_u32_e32 v157, v134, v143
	v_add_u32_e32 v159, v155, v143
	ds_read_b128 v[240:243], v157
	s_and_b32 s67, s65, 0x10000
	v_add_u32_e32 v176, s67, v141
	v_lshl_add_u64 v[174:175], v[168:169], 0, s[72:73]
	s_nop 0
	v_readfirstlane_b32 s67, v176
	s_mov_b64 s[76:77], 0x12c01080
	v_lshl_add_u64 v[176:177], v[174:175], 0, s[76:77]
	s_mov_b32 m0, s67
	s_nop 0
	global_load_lds_dwordx4 v[176:177], off
	v_mfma_f32_32x32x16_bf16 v[98:113], v[224:227], v[236:239], v[98:113]
	ds_read_b128 v[248:251], v159 offset:32768
	s_mov_b64 s[76:77], 0x12c21080
	v_lshl_add_u64 v[176:177], v[174:175], 0, s[76:77]
	s_add_i32 m0, s67, 0x2000
	s_nop 0
	global_load_lds_dwordx4 v[176:177], off
	s_mov_b64 s[76:77], 0x12c41080
	v_lshl_add_u64 v[176:177], v[174:175], 0, s[76:77]
	s_add_i32 m0, s67, 0x4000
	s_nop 0
	global_load_lds_dwordx4 v[176:177], off
	v_mfma_f32_32x32x16_bf16 v[82:97], v[228:231], v[232:235], v[82:97]
	ds_read_b128 v[252:255], v159 offset:36864
	s_mov_b64 s[76:77], 0x12c61080
	v_lshl_add_u64 v[176:177], v[174:175], 0, s[76:77]
	s_add_i32 m0, s67, 0x6000
	s_nop 0
	global_load_lds_dwordx4 v[176:177], off
	v_mfma_f32_32x32x16_bf16 v[50:65], v[228:231], v[236:239], v[50:65]
	ds_read_b128 v[244:247], v157 offset:4096
	v_lshl_add_u64 v[176:177], v[170:171], 0, s[72:73]
	s_add_i32 m0, s67, 0x8000
	s_nop 0
	global_load_lds_dwordx4 v[176:177], off
	v_lshl_add_u64 v[176:177], v[172:173], 0, s[72:73]
	s_add_i32 m0, s67, 0xa000
	s_nop 0
	global_load_lds_dwordx4 v[176:177], off
	s_add_u32 s72, s72, 0x80
	s_addc_u32 s73, s73, 0
	s_add_i32 s65, s65, 0x10000
	s_branch .Lp4b_kloop
.Lp4b_knodma:
	v_mfma_f32_32x32x16_bf16 v[114:129], v[224:227], v[232:235], v[114:129]
	v_add_u32_e32 v157, v134, v143
	v_add_u32_e32 v159, v155, v143
	ds_read_b128 v[240:243], v157
	v_mfma_f32_32x32x16_bf16 v[98:113], v[224:227], v[236:239], v[98:113]
	ds_read_b128 v[248:251], v159 offset:32768
	v_mfma_f32_32x32x16_bf16 v[82:97], v[228:231], v[232:235], v[82:97]
	ds_read_b128 v[252:255], v159 offset:36864
	v_mfma_f32_32x32x16_bf16 v[50:65], v[228:231], v[236:239], v[50:65]
	ds_read_b128 v[244:247], v157 offset:4096
	s_add_u32 s72, s72, 0x80
	s_addc_u32 s73, s73, 0
	s_add_i32 s65, s65, 0x10000
	s_branch .Lp4b_kloop

; #define MFMA(a, b, c) __builtin_amdgcn_mfma_f32_32x32x16_bf16((a), (b), (c), 0, 0, 0)
; #define GEMM_ISSUE(KT, ST) do { const int k1_ = (KT) << 6; unsigned char* d_ = ldst + (ST) * STAGE; \
;         _Pragma("unroll") for (int j_ = 0; j_ < 4; ++j_) dma16(ap + (size_t)(64 * j_) * lda + k1_, d_ + j_ * 8192); \
;         _Pragma("unroll") for (int j_ = 0; j_ < NBW; ++j_) dma16(bp + bro[j_] + k1_, d_ + BOFF + j_ * 8192); } while (0)
; template <int NBW>
; DI void gemm_mainloop(f32x16 (&acc)[2][NBW], const bf16_t* A, size_t lda, int m0, const bf16_t* Bt, size_t ldb, int n0, int K, unsigned char* lds, bool pre = false, bool only_issue = false) {
;     ...
;     for (int kt = 0; kt < nk; ++kt) {
;         const unsigned char* st = lds + (kt & 1) * STAGE;
; #pragma unroll
;         for (int s = 0; s < 4; ++s) {
;             if (s == 1 && kt + 1 < nk) GEMM_ISSUE(kt + 1, (kt + 1) & 1);
;             bf16x8 a[2], b[NBW];
; #pragma unroll
;             for (int mb = 0; mb < 2; ++mb) a[mb] = *(const bf16x8*)(st + aofs + mb * 4096 + xo[s]);
; #pragma unroll
;             for (int nb = 0; nb < NBW; ++nb) b[nb] = *(const bf16x8*)(st + bofs + nb * 4096 + xo[s]);
; #pragma unroll
;             for (int mb = 0; mb < 2; ++mb)
; #pragma unroll
;                 for (int nb = 0; nb < NBW; ++nb) acc[mb][nb] = MFMA(a[mb], b[nb], acc[mb][nb]);
;         }
;         __syncthreads();
.Lp5_kloop:
	s_waitcnt lgkmcnt(4)
	v_mfma_f32_32x32x16_bf16 v[114:129], v[224:227], v[232:235], v[114:129]
	v_add_u32_e32 v252, v147, v142
	v_add_u32_e32 v253, v148, v142
	ds_read_b128 v[150:153], v252
	s_waitcnt lgkmcnt(4)
	v_mfma_f32_32x32x16_bf16 v[98:113], v[224:227], v[236:239], v[98:113]
	ds_read_b128 v[158:161], v253 offset:32768
	s_waitcnt lgkmcnt(4)
	v_mfma_f32_32x32x16_bf16 v[82:97], v[224:227], v[240:243], v[82:97]
	ds_read_b128 v[170:173], v253 offset:36864
	s_waitcnt lgkmcnt(4)
	v_mfma_f32_32x32x16_bf16 v[66:81], v[224:227], v[244:247], v[66:81]
	ds_read_b128 v[174:177], v253 offset:40960
	s_waitcnt lgkmcnt(4)
	v_mfma_f32_32x32x16_bf16 v[50:65], v[228:231], v[232:235], v[50:65]
	ds_read_b128 v[178:181], v253 offset:45056
	v_mfma_f32_32x32x16_bf16 v[34:49], v[228:231], v[236:239], v[34:49]
	ds_read_b128 v[154:157], v252 offset:4096
	v_mfma_f32_32x32x16_bf16 v[18:33], v[228:231], v[240:243], v[18:33]
	v_mfma_f32_32x32x16_bf16 v[2:17], v[228:231], v[244:247], v[2:17]
	s_waitcnt lgkmcnt(4)
	v_mfma_f32_32x32x16_bf16 v[114:129], v[150:153], v[158:161], v[114:129]
	v_add_u32_e32 v252, v147, v143
	v_add_u32_e32 v253, v148, v143
	ds_read_b128 v[224:227], v252
	s_waitcnt lgkmcnt(4)
	v_mfma_f32_32x32x16_bf16 v[98:113], v[150:153], v[170:173], v[98:113]
	ds_read_b128 v[232:235], v253 offset:32768
	s_waitcnt lgkmcnt(4)
	v_mfma_f32_32x32x16_bf16 v[82:97], v[150:153], v[174:177], v[82:97]
	ds_read_b128 v[236:239], v253 offset:36864
	s_waitcnt lgkmcnt(4)
	v_mfma_f32_32x32x16_bf16 v[66:81], v[150:153], v[178:181], v[66:81]
	ds_read_b128 v[240:243], v253 offset:40960
	s_waitcnt lgkmcnt(4)
	v_mfma_f32_32x32x16_bf16 v[50:65], v[154:157], v[158:161], v[50:65]
	ds_read_b128 v[244:247], v253 offset:45056
	v_mfma_f32_32x32x16_bf16 v[34:49], v[154:157], v[170:173], v[34:49]
	ds_read_b128 v[228:231], v252 offset:4096
	v_mfma_f32_32x32x16_bf16 v[18:33], v[154:157], v[174:177], v[18:33]
	v_mfma_f32_32x32x16_bf16 v[2:17], v[154:157], v[178:181], v[2:17]
	s_waitcnt lgkmcnt(4)
	v_mfma_f32_32x32x16_bf16 v[114:129], v[224:227], v[232:235], v[114:129]
	v_add_u32_e32 v252, v147, v144
	v_add_u32_e32 v253, v148, v144
	ds_read_b128 v[150:153], v252
	s_waitcnt lgkmcnt(4)
	v_mfma_f32_32x32x16_bf16 v[98:113], v[224:227], v[236:239], v[98:113]
	ds_read_b128 v[158:161], v253 offset:32768
	s_waitcnt lgkmcnt(4)
	v_mfma_f32_32x32x16_bf16 v[82:97], v[224:227], v[240:243], v[82:97]
	ds_read_b128 v[170:173], v253 offset:36864
	s_waitcnt lgkmcnt(4)
	v_mfma_f32_32x32x16_bf16 v[66:81], v[224:227], v[244:247], v[66:81]
	ds_read_b128 v[174:177], v253 offset:40960
	s_waitcnt lgkmcnt(4)
	v_mfma_f32_32x32x16_bf16 v[50:65], v[228:231], v[232:235], v[50:65]
	ds_read_b128 v[178:181], v253 offset:45056
	v_mfma_f32_32x32x16_bf16 v[34:49], v[228:231], v[236:239], v[34:49]
	ds_read_b128 v[154:157], v252 offset:4096
	v_mfma_f32_32x32x16_bf16 v[18:33], v[228:231], v[240:243], v[18:33]
	v_mfma_f32_32x32x16_bf16 v[2:17], v[228:231], v[244:247], v[2:17]
	v_xor_b32_e32 v147, 0x10000, v147
	v_xor_b32_e32 v148, 0x10000, v148
	s_waitcnt vmcnt(0) lgkmcnt(0)
	s_barrier
	s_cmp_eq_u32 s22, 0x800
	s_cbranch_scc1 .Lp5_klast
	s_cmp_eq_u32 s22, 0x780
	s_cbranch_scc1 .Lp5_knodma
	v_mfma_f32_32x32x16_bf16 v[114:129], v[150:153], v[158:161], v[114:129]
	v_add_u32_e32 v252, v147, v141
	v_add_u32_e32 v253, v148, v141
	ds_read_b128 v[224:227], v252
	s_and_b32 s29, s27, 0x10000
	v_add_u32_e32 v250, s29, v140
	v_lshl_add_u64 v[248:249], v[130:131], 0, s[22:23]
	s_nop 0
	v_readfirstlane_b32 s29, v250
	v_lshl_add_u64 v[250:251], v[248:249], 0, s[14:15]
	s_mov_b32 m0, s29
	s_nop 0
	global_load_lds_dwordx4 v[250:251], off
	v_mfma_f32_32x32x16_bf16 v[98:113], v[150:153], v[170:173], v[98:113]
	ds_read_b128 v[232:235], v253 offset:32768
	v_lshl_add_u64 v[250:251], v[248:249], 0, s[16:17]
	s_add_i32 m0, s29, 0x2000
	s_nop 0
	global_load_lds_dwordx4 v[250:251], off
	v_mfma_f32_32x32x16_bf16 v[82:97], v[150:153], v[174:177], v[82:97]
	ds_read_b128 v[236:239], v253 offset:36864
	v_lshl_add_u64 v[250:251], v[248:249], 0, s[18:19]
	s_add_i32 m0, s29, 0x4000
	s_nop 0
	global_load_lds_dwordx4 v[250:251], off
	v_mfma_f32_32x32x16_bf16 v[66:81], v[150:153], v[178:181], v[66:81]
	ds_read_b128 v[240:243], v253 offset:40960
	v_lshl_add_u64 v[250:251], v[248:249], 0, s[20:21]
	s_add_i32 m0, s29, 0x6000
	s_nop 0
	global_load_lds_dwordx4 v[250:251], off
	v_mfma_f32_32x32x16_bf16 v[50:65], v[154:157], v[158:161], v[50:65]
	ds_read_b128 v[244:247], v253 offset:45056
	v_lshl_add_u64 v[250:251], v[132:133], 0, s[22:23]
	s_add_i32 m0, s29, 0x8000
	s_nop 0
	global_load_lds_dwordx4 v[250:251], off
	v_mfma_f32_32x32x16_bf16 v[34:49], v[154:157], v[170:173], v[34:49]
	ds_read_b128 v[228:231], v252 offset:4096
	v_lshl_add_u64 v[250:251], v[134:135], 0, s[22:23]
	s_add_i32 m0, s29, 0xa000
	s_nop 0
	global_load_lds_dwordx4 v[250:251], off
	v_mfma_f32_32x32x16_bf16 v[18:33], v[154:157], v[174:177], v[18:33]
	v_lshl_add_u64 v[250:251], v[136:137], 0, s[22:23]
	s_add_i32 m0, s29, 0xc000
	s_nop 0
	global_load_lds_dwordx4 v[250:251], off
	v_mfma_f32_32x32x16_bf16 v[2:17], v[154:157], v[178:181], v[2:17]
	v_lshl_add_u64 v[250:251], v[138:139], 0, s[22:23]
	s_add_i32 m0, s29, 0xe000
	s_nop 0
	global_load_lds_dwordx4 v[250:251], off
	s_add_u32 s22, s22, 0x80
	s_addc_u32 s23, s23, 0
	s_add_i32 s27, s27, 0x10000
	s_branch .Lp5_kloop
.Lp5_knodma:
	v_mfma_f32_32x32x16_bf16 v[114:129], v[150:153], v[158:161], v[114:129]
	v_add_u32_e32 v252, v147, v141
	v_add_u32_e32 v253, v148, v141
	ds_read_b128 v[224:227], v252
	v_mfma_f32_32x32x16_bf16 v[98:113], v[150:153], v[170:173], v[98:113]
	ds_read_b128 v[232:235], v253 offset:32768
	v_mfma_f32_32x32x16_bf16 v[82:97], v[150:153], v[174:177], v[82:97]
	ds_read_b128 v[236:239], v253 offset:36864
	v_mfma_f32_32x32x16_bf16 v[66:81], v[150:153], v[178:181], v[66:81]
	ds_read_b128 v[240:243], v253 offset:40960
	v_mfma_f32_32x32x16_bf16 v[50:65], v[154:157], v[158:161], v[50:65]
	ds_read_b128 v[244:247], v253 offset:45056
	v_mfma_f32_32x32x16_bf16 v[34:49], v[154:157], v[170:173], v[34:49]
	ds_read_b128 v[228:231], v252 offset:4096
	v_mfma_f32_32x32x16_bf16 v[18:33], v[154:157], v[174:177], v[18:33]
	v_mfma_f32_32x32x16_bf16 v[2:17], v[154:157], v[178:181], v[2:17]
	s_add_u32 s22, s22, 0x80
	s_addc_u32 s23, s23, 0
	s_add_i32 s27, s27, 0x10000
	s_branch .Lp5_kloop

; #define MFMA(a, b, c) __builtin_amdgcn_mfma_f32_32x32x16_bf16((a), (b), (c), 0, 0, 0)
; #define GEMM_ISSUE(KT, ST) do { const int k1_ = (KT) << 6; unsigned char* d_ = ldst + (ST) * STAGE; \
;         _Pragma("unroll") for (int j_ = 0; j_ < 4; ++j_) dma16(ap + (size_t)(64 * j_) * lda + k1_, d_ + j_ * 8192); \
;         _Pragma("unroll") for (int j_ = 0; j_ < NBW; ++j_) dma16(bp + bro[j_] + k1_, d_ + BOFF + j_ * 8192); } while (0)
; template <int NBW>
; DI void gemm_mainloop(f32x16 (&acc)[2][NBW], const bf16_t* A, size_t lda, int m0, const bf16_t* Bt, size_t ldb, int n0, int K, unsigned char* lds, bool pre = false, bool only_issue = false) {
;     ...
;     for (int kt = 0; kt < nk; ++kt) {
;         const unsigned char* st = lds + (kt & 1) * STAGE;
; #pragma unroll
;         for (int s = 0; s < 4; ++s) {
;             if (s == 1 && kt + 1 < nk) GEMM_ISSUE(kt + 1, (kt + 1) & 1);
;             bf16x8 a[2], b[NBW];
; #pragma unroll
;             for (int mb = 0; mb < 2; ++mb) a[mb] = *(const bf16x8*)(st + aofs + mb * 4096 + xo[s]);
; #pragma unroll
;             for (int nb = 0; nb < NBW; ++nb) b[nb] = *(const bf16x8*)(st + bofs + nb * 4096 + xo[s]);
; #pragma unroll
;             for (int mb = 0; mb < 2; ++mb)
; #pragma unroll
;                 for (int nb = 0; nb < NBW; ++nb) acc[mb][nb] = MFMA(a[mb], b[nb], acc[mb][nb]);
;         }
;         __syncthreads();
.Lp6_kloop:
	s_waitcnt lgkmcnt(4)
	v_mfma_f32_32x32x16_bf16 v[114:129], v[224:227], v[232:235], v[114:129]
	v_add_u32_e32 v252, v132, v166
	v_add_u32_e32 v253, v171, v166
	ds_read_b128 v[172:175], v252
	s_waitcnt lgkmcnt(4)
	v_mfma_f32_32x32x16_bf16 v[98:113], v[224:227], v[236:239], v[98:113]
	ds_read_b128 v[180:183], v253 offset:32768
	s_waitcnt lgkmcnt(4)
	v_mfma_f32_32x32x16_bf16 v[82:97], v[224:227], v[240:243], v[82:97]
	ds_read_b128 v[184:187], v253 offset:36864
	s_waitcnt lgkmcnt(4)
	v_mfma_f32_32x32x16_bf16 v[66:81], v[224:227], v[244:247], v[66:81]
	ds_read_b128 v[188:191], v253 offset:40960
	s_waitcnt lgkmcnt(4)
	v_mfma_f32_32x32x16_bf16 v[50:65], v[228:231], v[232:235], v[50:65]
	ds_read_b128 v[192:195], v253 offset:45056
	v_mfma_f32_32x32x16_bf16 v[34:49], v[228:231], v[236:239], v[34:49]
	ds_read_b128 v[176:179], v252 offset:4096
	v_mfma_f32_32x32x16_bf16 v[18:33], v[228:231], v[240:243], v[18:33]
	v_mfma_f32_32x32x16_bf16 v[2:17], v[228:231], v[244:247], v[2:17]
	s_waitcnt lgkmcnt(4)
	v_mfma_f32_32x32x16_bf16 v[114:129], v[172:175], v[180:183], v[114:129]
	v_add_u32_e32 v252, v132, v167
	v_add_u32_e32 v253, v171, v167
	ds_read_b128 v[224:227], v252
	s_waitcnt lgkmcnt(4)
	v_mfma_f32_32x32x16_bf16 v[98:113], v[172:175], v[184:187], v[98:113]
	ds_read_b128 v[232:235], v253 offset:32768
	s_waitcnt lgkmcnt(4)
	v_mfma_f32_32x32x16_bf16 v[82:97], v[172:175], v[188:191], v[82:97]
	ds_read_b128 v[236:239], v253 offset:36864
	s_waitcnt lgkmcnt(4)
	v_mfma_f32_32x32x16_bf16 v[66:81], v[172:175], v[192:195], v[66:81]
	ds_read_b128 v[240:243], v253 offset:40960
	s_waitcnt lgkmcnt(4)
	v_mfma_f32_32x32x16_bf16 v[50:65], v[176:179], v[180:183], v[50:65]
	ds_read_b128 v[244:247], v253 offset:45056
	v_mfma_f32_32x32x16_bf16 v[34:49], v[176:179], v[184:187], v[34:49]
	ds_read_b128 v[228:231], v252 offset:4096
	v_mfma_f32_32x32x16_bf16 v[18:33], v[176:179], v[188:191], v[18:33]
	v_mfma_f32_32x32x16_bf16 v[2:17], v[176:179], v[192:195], v[2:17]
	s_waitcnt lgkmcnt(4)
	v_mfma_f32_32x32x16_bf16 v[114:129], v[224:227], v[232:235], v[114:129]
	v_add_u32_e32 v252, v132, v168
	v_add_u32_e32 v253, v171, v168
	ds_read_b128 v[172:175], v252
	s_waitcnt lgkmcnt(4)
	v_mfma_f32_32x32x16_bf16 v[98:113], v[224:227], v[236:239], v[98:113]
	ds_read_b128 v[180:183], v253 offset:32768
	s_waitcnt lgkmcnt(4)
	v_mfma_f32_32x32x16_bf16 v[82:97], v[224:227], v[240:243], v[82:97]
	ds_read_b128 v[184:187], v253 offset:36864
	s_waitcnt lgkmcnt(4)
	v_mfma_f32_32x32x16_bf16 v[66:81], v[224:227], v[244:247], v[66:81]
	ds_read_b128 v[188:191], v253 offset:40960
	s_waitcnt lgkmcnt(4)
	v_mfma_f32_32x32x16_bf16 v[50:65], v[228:231], v[232:235], v[50:65]
	ds_read_b128 v[192:195], v253 offset:45056
	v_mfma_f32_32x32x16_bf16 v[34:49], v[228:231], v[236:239], v[34:49]
	ds_read_b128 v[176:179], v252 offset:4096
	v_mfma_f32_32x32x16_bf16 v[18:33], v[228:231], v[240:243], v[18:33]
	v_mfma_f32_32x32x16_bf16 v[2:17], v[228:231], v[244:247], v[2:17]
	v_xor_b32_e32 v132, 0x10000, v132
	v_xor_b32_e32 v171, 0x10000, v171
	s_waitcnt vmcnt(0) lgkmcnt(0)
	s_barrier
	s_cmp_eq_u32 s28, 0x800
	s_cbranch_scc1 .Lp6_klast
	s_cmp_eq_u32 s28, 0x780
	s_cbranch_scc1 .Lp6_knodma
	v_mfma_f32_32x32x16_bf16 v[114:129], v[172:175], v[180:183], v[114:129]
	v_add_u32_e32 v252, v132, v165
	v_add_u32_e32 v253, v171, v165
	ds_read_b128 v[224:227], v252
	s_and_b32 s30, s27, 0x10000
	v_add_u32_e32 v250, s30, v164
	v_lshl_add_u64 v[248:249], v[134:135], 0, s[28:29]
	s_nop 0
	v_readfirstlane_b32 s30, v250
	v_lshl_add_u64 v[250:251], v[248:249], 0, s[16:17]
	s_mov_b32 m0, s30
	s_nop 0
	global_load_lds_dwordx4 v[250:251], off
	v_mfma_f32_32x32x16_bf16 v[98:113], v[172:175], v[184:187], v[98:113]
	ds_read_b128 v[232:235], v253 offset:32768
	v_lshl_add_u64 v[250:251], v[248:249], 0, s[18:19]
	s_add_i32 m0, s30, 0x2000
	s_nop 0
	global_load_lds_dwordx4 v[250:251], off
	v_mfma_f32_32x32x16_bf16 v[82:97], v[172:175], v[188:191], v[82:97]
	ds_read_b128 v[236:239], v253 offset:36864
	v_lshl_add_u64 v[250:251], v[248:249], 0, s[20:21]
	s_add_i32 m0, s30, 0x4000
	s_nop 0
	global_load_lds_dwordx4 v[250:251], off
	v_mfma_f32_32x32x16_bf16 v[66:81], v[172:175], v[192:195], v[66:81]
	ds_read_b128 v[240:243], v253 offset:40960
	v_lshl_add_u64 v[250:251], v[248:249], 0, s[22:23]
	s_add_i32 m0, s30, 0x6000
	s_nop 0
	global_load_lds_dwordx4 v[250:251], off
	v_mfma_f32_32x32x16_bf16 v[50:65], v[176:179], v[180:183], v[50:65]
	ds_read_b128 v[244:247], v253 offset:45056
	v_lshl_add_u64 v[250:251], v[136:137], 0, s[28:29]
	s_add_i32 m0, s30, 0x8000
	s_nop 0
	global_load_lds_dwordx4 v[250:251], off
	v_mfma_f32_32x32x16_bf16 v[34:49], v[176:179], v[184:187], v[34:49]
	ds_read_b128 v[228:231], v252 offset:4096
	v_lshl_add_u64 v[250:251], v[138:139], 0, s[28:29]
	s_add_i32 m0, s30, 0xa000
	s_nop 0
	global_load_lds_dwordx4 v[250:251], off
	v_mfma_f32_32x32x16_bf16 v[18:33], v[176:179], v[188:191], v[18:33]
	v_lshl_add_u64 v[250:251], v[140:141], 0, s[28:29]
	s_add_i32 m0, s30, 0xc000
	s_nop 0
	global_load_lds_dwordx4 v[250:251], off
	v_mfma_f32_32x32x16_bf16 v[2:17], v[176:179], v[192:195], v[2:17]
	v_lshl_add_u64 v[250:251], v[142:143], 0, s[28:29]
	s_add_i32 m0, s30, 0xe000
	s_nop 0
	global_load_lds_dwordx4 v[250:251], off
	s_add_u32 s28, s28, 0x80
	s_addc_u32 s29, s29, 0
	s_add_i32 s27, s27, 0x10000
	s_branch .Lp6_kloop
.Lp6_knodma:
	v_mfma_f32_32x32x16_bf16 v[114:129], v[172:175], v[180:183], v[114:129]
	v_add_u32_e32 v252, v132, v165
	v_add_u32_e32 v253, v171, v165
	ds_read_b128 v[224:227], v252
	v_mfma_f32_32x32x16_bf16 v[98:113], v[172:175], v[184:187], v[98:113]
	ds_read_b128 v[232:235], v253 offset:32768
	v_mfma_f32_32x32x16_bf16 v[82:97], v[172:175], v[188:191], v[82:97]
	ds_read_b128 v[236:239], v253 offset:36864
	v_mfma_f32_32x32x16_bf16 v[66:81], v[172:175], v[192:195], v[66:81]
	ds_read_b128 v[240:243], v253 offset:40960
	v_mfma_f32_32x32x16_bf16 v[50:65], v[176:179], v[180:183], v[50:65]
	ds_read_b128 v[244:247], v253 offset:45056
	v_mfma_f32_32x32x16_bf16 v[34:49], v[176:179], v[184:187], v[34:49]
	ds_read_b128 v[228:231], v252 offset:4096
	v_mfma_f32_32x32x16_bf16 v[18:33], v[176:179], v[188:191], v[18:33]
	v_mfma_f32_32x32x16_bf16 v[2:17], v[176:179], v[192:195], v[2:17]
	s_add_u32 s28, s28, 0x80
	s_addc_u32 s29, s29, 0
	s_add_i32 s27, s27, 0x10000
	s_branch .Lp6_kloop

; #define MFMA(a, b, c) __builtin_amdgcn_mfma_f32_32x32x16_bf16((a), (b), (c), 0, 0, 0)
; #define GEMM_ISSUE(KT, ST) do { const int k1_ = (KT) << 6; unsigned char* d_ = ldst + (ST) * STAGE; \
;         _Pragma("unroll") for (int j_ = 0; j_ < 4; ++j_) dma16(ap + (size_t)(64 * j_) * lda + k1_, d_ + j_ * 8192); \
;         _Pragma("unroll") for (int j_ = 0; j_ < NBW; ++j_) dma16(bp + bro[j_] + k1_, d_ + BOFF + j_ * 8192); } while (0)
; template <int NBW>
; DI void gemm_mainloop(f32x16 (&acc)[2][NBW], const bf16_t* A, size_t lda, int m0, const bf16_t* Bt, size_t ldb, int n0, int K, unsigned char* lds, bool pre = false, bool only_issue = false) {
;     ...
;     for (int kt = 0; kt < nk; ++kt) {
;         const unsigned char* st = lds + (kt & 1) * STAGE;
; #pragma unroll
;         for (int s = 0; s < 4; ++s) {
;             if (s == 1 && kt + 1 < nk) GEMM_ISSUE(kt + 1, (kt + 1) & 1);
;             bf16x8 a[2], b[NBW];
; #pragma unroll
;             for (int mb = 0; mb < 2; ++mb) a[mb] = *(const bf16x8*)(st + aofs + mb * 4096 + xo[s]);
; #pragma unroll
;             for (int nb = 0; nb < NBW; ++nb) b[nb] = *(const bf16x8*)(st + bofs + nb * 4096 + xo[s]);
; #pragma unroll
;             for (int mb = 0; mb < 2; ++mb)
; #pragma unroll
;                 for (int nb = 0; nb < NBW; ++nb) acc[mb][nb] = MFMA(a[mb], b[nb], acc[mb][nb]);
;         }
;         __syncthreads();
.Lp7_kloop:
	s_waitcnt lgkmcnt(4)
	v_mfma_f32_32x32x16_bf16 v[114:129], v[224:227], v[232:235], v[114:129]
	v_add_u32_e32 v252, v132, v149
	v_add_u32_e32 v253, v154, v149
	ds_read_b128 v[156:159], v252
	s_waitcnt lgkmcnt(4)
	v_mfma_f32_32x32x16_bf16 v[98:113], v[224:227], v[236:239], v[98:113]
	ds_read_b128 v[164:167], v253 offset:32768
	s_waitcnt lgkmcnt(4)
	v_mfma_f32_32x32x16_bf16 v[82:97], v[224:227], v[240:243], v[82:97]
	ds_read_b128 v[168:171], v253 offset:36864
	s_waitcnt lgkmcnt(4)
	v_mfma_f32_32x32x16_bf16 v[66:81], v[224:227], v[244:247], v[66:81]
	ds_read_b128 v[172:175], v253 offset:40960
	s_waitcnt lgkmcnt(4)
	v_mfma_f32_32x32x16_bf16 v[50:65], v[228:231], v[232:235], v[50:65]
	ds_read_b128 v[176:179], v253 offset:45056
	v_mfma_f32_32x32x16_bf16 v[34:49], v[228:231], v[236:239], v[34:49]
	ds_read_b128 v[160:163], v252 offset:4096
	v_mfma_f32_32x32x16_bf16 v[18:33], v[228:231], v[240:243], v[18:33]
	v_mfma_f32_32x32x16_bf16 v[2:17], v[228:231], v[244:247], v[2:17]
	s_waitcnt lgkmcnt(4)
	v_mfma_f32_32x32x16_bf16 v[114:129], v[156:159], v[164:167], v[114:129]
	v_add_u32_e32 v252, v132, v150
	v_add_u32_e32 v253, v154, v150
	ds_read_b128 v[224:227], v252
	s_waitcnt lgkmcnt(4)
	v_mfma_f32_32x32x16_bf16 v[98:113], v[156:159], v[168:171], v[98:113]
	ds_read_b128 v[232:235], v253 offset:32768
	s_waitcnt lgkmcnt(4)
	v_mfma_f32_32x32x16_bf16 v[82:97], v[156:159], v[172:175], v[82:97]
	ds_read_b128 v[236:239], v253 offset:36864
	s_waitcnt lgkmcnt(4)
	v_mfma_f32_32x32x16_bf16 v[66:81], v[156:159], v[176:179], v[66:81]
	ds_read_b128 v[240:243], v253 offset:40960
	s_waitcnt lgkmcnt(4)
	v_mfma_f32_32x32x16_bf16 v[50:65], v[160:163], v[164:167], v[50:65]
	ds_read_b128 v[244:247], v253 offset:45056
	v_mfma_f32_32x32x16_bf16 v[34:49], v[160:163], v[168:171], v[34:49]
	ds_read_b128 v[228:231], v252 offset:4096
	v_mfma_f32_32x32x16_bf16 v[18:33], v[160:163], v[172:175], v[18:33]
	v_mfma_f32_32x32x16_bf16 v[2:17], v[160:163], v[176:179], v[2:17]
	s_waitcnt lgkmcnt(4)
	v_mfma_f32_32x32x16_bf16 v[114:129], v[224:227], v[232:235], v[114:129]
	v_add_u32_e32 v252, v132, v151
	v_add_u32_e32 v253, v154, v151
	ds_read_b128 v[156:159], v252
	s_waitcnt lgkmcnt(4)
	v_mfma_f32_32x32x16_bf16 v[98:113], v[224:227], v[236:239], v[98:113]
	ds_read_b128 v[164:167], v253 offset:32768
	s_waitcnt lgkmcnt(4)
	v_mfma_f32_32x32x16_bf16 v[82:97], v[224:227], v[240:243], v[82:97]
	ds_read_b128 v[168:171], v253 offset:36864
	s_waitcnt lgkmcnt(4)
	v_mfma_f32_32x32x16_bf16 v[66:81], v[224:227], v[244:247], v[66:81]
	ds_read_b128 v[172:175], v253 offset:40960
	s_waitcnt lgkmcnt(4)
	v_mfma_f32_32x32x16_bf16 v[50:65], v[228:231], v[232:235], v[50:65]
	ds_read_b128 v[176:179], v253 offset:45056
	v_mfma_f32_32x32x16_bf16 v[34:49], v[228:231], v[236:239], v[34:49]
	ds_read_b128 v[160:163], v252 offset:4096
	v_mfma_f32_32x32x16_bf16 v[18:33], v[228:231], v[240:243], v[18:33]
	v_mfma_f32_32x32x16_bf16 v[2:17], v[228:231], v[244:247], v[2:17]
	v_xor_b32_e32 v132, 0x10000, v132
	v_xor_b32_e32 v154, 0x10000, v154
	s_waitcnt vmcnt(0) lgkmcnt(0)
	s_barrier
	s_cmp_eq_u32 s22, 0x2000
	s_cbranch_scc1 .Lp7_klast
	s_cmp_eq_u32 s22, 0x1f80
	s_cbranch_scc1 .Lp7_knodma
	v_mfma_f32_32x32x16_bf16 v[114:129], v[156:159], v[164:167], v[114:129]
	v_add_u32_e32 v252, v132, v148
	v_add_u32_e32 v253, v154, v148
	ds_read_b128 v[224:227], v252
	s_and_b32 s24, s21, 0x10000
	v_add_u32_e32 v250, s24, v147
	v_lshl_add_u64 v[248:249], v[134:135], 0, s[22:23]
	s_nop 0
	v_readfirstlane_b32 s24, v250
	v_lshl_add_u64 v[250:251], v[248:249], 0, s[10:11]
	s_mov_b32 m0, s24
	s_nop 0
	global_load_lds_dwordx4 v[250:251], off
	v_mfma_f32_32x32x16_bf16 v[98:113], v[156:159], v[168:171], v[98:113]
	ds_read_b128 v[232:235], v253 offset:32768
	v_lshl_add_u64 v[250:251], v[248:249], 0, s[12:13]
	s_add_i32 m0, s24, 0x2000
	s_nop 0
	global_load_lds_dwordx4 v[250:251], off
	v_mfma_f32_32x32x16_bf16 v[82:97], v[156:159], v[172:175], v[82:97]
	ds_read_b128 v[236:239], v253 offset:36864
	v_lshl_add_u64 v[250:251], v[248:249], 0, s[14:15]
	s_add_i32 m0, s24, 0x4000
	s_nop 0
	global_load_lds_dwordx4 v[250:251], off
	v_mfma_f32_32x32x16_bf16 v[66:81], v[156:159], v[176:179], v[66:81]
	ds_read_b128 v[240:243], v253 offset:40960
	v_lshl_add_u64 v[250:251], v[248:249], 0, s[16:17]
	s_add_i32 m0, s24, 0x6000
	s_nop 0
	global_load_lds_dwordx4 v[250:251], off
	v_mfma_f32_32x32x16_bf16 v[50:65], v[160:163], v[164:167], v[50:65]
	ds_read_b128 v[244:247], v253 offset:45056
	v_lshl_add_u64 v[250:251], v[136:137], 0, s[22:23]
	s_add_i32 m0, s24, 0x8000
	s_nop 0
	global_load_lds_dwordx4 v[250:251], off
	v_mfma_f32_32x32x16_bf16 v[34:49], v[160:163], v[168:171], v[34:49]
	ds_read_b128 v[228:231], v252 offset:4096
	v_lshl_add_u64 v[250:251], v[138:139], 0, s[22:23]
	s_add_i32 m0, s24, 0xa000
	s_nop 0
	global_load_lds_dwordx4 v[250:251], off
	v_mfma_f32_32x32x16_bf16 v[18:33], v[160:163], v[172:175], v[18:33]
	v_lshl_add_u64 v[250:251], v[140:141], 0, s[22:23]
	s_add_i32 m0, s24, 0xc000
	s_nop 0
	global_load_lds_dwordx4 v[250:251], off
	v_mfma_f32_32x32x16_bf16 v[2:17], v[160:163], v[176:179], v[2:17]
	v_lshl_add_u64 v[250:251], v[142:143], 0, s[22:23]
	s_add_i32 m0, s24, 0xe000
	s_nop 0
	global_load_lds_dwordx4 v[250:251], off
	s_add_u32 s22, s22, 0x80
	s_addc_u32 s23, s23, 0
	s_add_i32 s21, s21, 0x10000
	s_branch .Lp7_kloop
.Lp7_knodma:
	v_mfma_f32_32x32x16_bf16 v[114:129], v[156:159], v[164:167], v[114:129]
	v_add_u32_e32 v252, v132, v148
	v_add_u32_e32 v253, v154, v148
	ds_read_b128 v[224:227], v252
	v_mfma_f32_32x32x16_bf16 v[98:113], v[156:159], v[168:171], v[98:113]
	ds_read_b128 v[232:235], v253 offset:32768
	v_mfma_f32_32x32x16_bf16 v[82:97], v[156:159], v[172:175], v[82:97]
	ds_read_b128 v[236:239], v253 offset:36864
	v_mfma_f32_32x32x16_bf16 v[66:81], v[156:159], v[176:179], v[66:81]
	ds_read_b128 v[240:243], v253 offset:40960
	v_mfma_f32_32x32x16_bf16 v[50:65], v[160:163], v[164:167], v[50:65]
	ds_read_b128 v[244:247], v253 offset:45056
	v_mfma_f32_32x32x16_bf16 v[34:49], v[160:163], v[168:171], v[34:49]
	ds_read_b128 v[228:231], v252 offset:4096
	v_mfma_f32_32x32x16_bf16 v[18:33], v[160:163], v[172:175], v[18:33]
	v_mfma_f32_32x32x16_bf16 v[2:17], v[160:163], v[176:179], v[2:17]
	s_add_u32 s22, s22, 0x80
	s_addc_u32 s23, s23, 0
	s_add_i32 s21, s21, 0x10000
	s_branch .Lp7_kloop
